# group start stagger 2.5x larger (s_sleep 10 per index step)
# speedup vs baseline: 1.0316x; 1.0149x over previous
; __device__ __forceinline__ void mk_p3(const Ptrs& P, LAS unsigned char* lds, int tid, int wave, int lane, int bx, int G, bool dry) {
;     ...
;         { bool pre = false; for (int u = bx; u < NB * 32 * 4; u += G) pre = attn_unit(P, lds, u, tid, wave, lane, pre, u + G < NB * 32 * 4 ? u + G : -1); }
.Lstg_loop:
	s_cmp_eq_u32 vcc_lo, 0
	s_cbranch_scc1 .Lstg_done
	s_sleep 10
	s_sub_u32 vcc_lo, vcc_lo, 1
	s_branch .Lstg_loop
